# L2 GEMM epilogue stores with agent-scope write-through (sc1 only)
# speedup vs baseline: 1.0080x; 1.0010x over previous
.Lg2_loop:
	s_add_u32 s54, s54, 0x80
	s_addc_u32 s55, s55, 0
	s_add_u32 s56, s56, 0x80
	s_addc_u32 s57, s57, 0
	ds_read_b128 v[64:67], v156
	ds_read_b128 v[68:71], v158 offset:16384
	ds_read_b128 v[80:83], v159 offset:16384
	ds_read_b128 v[72:75], v157
	ds_read_b128 v[76:79], v158 offset:18432
	ds_read_b128 v[92:95], v159 offset:18432
	ds_read_b128 v[84:87], v158 offset:20480
	ds_read_b128 v[116:119], v159 offset:20480
	ds_read_b128 v[88:91], v158 offset:22528
	ds_read_b128 v[120:123], v159 offset:22528
	s_waitcnt lgkmcnt(8)
	v_mfma_f32_16x16x32_bf16 v[36:39], v[64:67], v[68:71], v[36:39]
	s_waitcnt lgkmcnt(5)
	v_mfma_f32_16x16x32_bf16 v[32:35], v[64:67], v[76:79], v[32:35]
	s_waitcnt lgkmcnt(3)
	s_add_u32 m0, s58, 0x8000
	v_mfma_f32_16x16x32_bf16 v[28:31], v[64:67], v[84:87], v[28:31]
	global_load_lds_dwordx4 v152, s[54:55]
	s_waitcnt lgkmcnt(1)
	v_mfma_f32_16x16x32_bf16 v[24:27], v[64:67], v[88:91], v[24:27]
	ds_read_b128 v[64:67], v156 offset:2048
	ds_read_b128 v[124:127], v157 offset:2048
	s_waitcnt lgkmcnt(1)
	v_mfma_f32_16x16x32_bf16 v[8:11], v[64:67], v[68:71], v[8:11]
	s_add_u32 m0, m0, 0x400
	v_mfma_f32_16x16x32_bf16 v[4:7], v[64:67], v[76:79], v[4:7]
	global_load_lds_dwordx4 v153, s[54:55]
	v_mfma_f32_16x16x32_bf16 v[0:3], v[64:67], v[84:87], v[0:3]
	v_mfma_f32_16x16x32_bf16 v[20:23], v[64:67], v[88:91], v[20:23]
	ds_read_b128 v[64:67], v156 offset:4096
	ds_read_b128 v[128:131], v157 offset:4096
	s_waitcnt lgkmcnt(1)
	s_add_u32 m0, m0, 0x400
	v_mfma_f32_16x16x32_bf16 v[12:15], v[64:67], v[68:71], v[12:15]
	global_load_lds_dwordx4 v154, s[54:55]
	v_mfma_f32_16x16x32_bf16 v[16:19], v[64:67], v[76:79], v[16:19]
	v_mfma_f32_16x16x32_bf16 v[56:59], v[64:67], v[84:87], v[56:59]
	s_add_u32 m0, m0, 0x400
	v_mfma_f32_16x16x32_bf16 v[52:55], v[64:67], v[88:91], v[52:55]
	global_load_lds_dwordx4 v155, s[54:55]
	ds_read_b128 v[64:67], v156 offset:6144
	ds_read_b128 v[132:135], v157 offset:6144
	s_waitcnt lgkmcnt(1)
	v_mfma_f32_16x16x32_bf16 v[48:51], v[64:67], v[68:71], v[48:51]
	v_mfma_f32_16x16x32_bf16 v[44:47], v[64:67], v[76:79], v[44:47]
	s_add_u32 m0, m0, 0x3400
	v_mfma_f32_16x16x32_bf16 v[40:43], v[64:67], v[84:87], v[40:43]
	global_load_lds_dwordx4 v152, s[56:57]
	v_mfma_f32_16x16x32_bf16 v[60:63], v[64:67], v[88:91], v[60:63]
	v_mfma_f32_16x16x32_bf16 v[36:39], v[72:75], v[80:83], v[36:39]
	s_add_u32 m0, m0, 0x400
	v_mfma_f32_16x16x32_bf16 v[32:35], v[72:75], v[92:95], v[32:35]
	global_load_lds_dwordx4 v153, s[56:57]
	v_mfma_f32_16x16x32_bf16 v[28:31], v[72:75], v[116:119], v[28:31]
	v_mfma_f32_16x16x32_bf16 v[24:27], v[72:75], v[120:123], v[24:27]
	s_add_u32 m0, m0, 0x400
	v_mfma_f32_16x16x32_bf16 v[8:11], v[124:127], v[80:83], v[8:11]
	global_load_lds_dwordx4 v154, s[56:57]
	v_mfma_f32_16x16x32_bf16 v[4:7], v[124:127], v[92:95], v[4:7]
	v_mfma_f32_16x16x32_bf16 v[0:3], v[124:127], v[116:119], v[0:3]
	s_add_u32 m0, m0, 0x400
	v_mfma_f32_16x16x32_bf16 v[20:23], v[124:127], v[120:123], v[20:23]
	global_load_lds_dwordx4 v155, s[56:57]
	v_mfma_f32_16x16x32_bf16 v[12:15], v[128:131], v[80:83], v[12:15]
	s_waitcnt lgkmcnt(0)
	v_mfma_f32_16x16x32_bf16 v[48:51], v[132:135], v[80:83], v[48:51]
	v_mfma_f32_16x16x32_bf16 v[16:19], v[128:131], v[92:95], v[16:19]
	v_mfma_f32_16x16x32_bf16 v[44:47], v[132:135], v[92:95], v[44:47]
	v_mfma_f32_16x16x32_bf16 v[56:59], v[128:131], v[116:119], v[56:59]
	v_mfma_f32_16x16x32_bf16 v[52:55], v[128:131], v[120:123], v[52:55]
	v_mfma_f32_16x16x32_bf16 v[40:43], v[132:135], v[116:119], v[40:43]
	v_mfma_f32_16x16x32_bf16 v[60:63], v[132:135], v[120:123], v[60:63]
	s_waitcnt vmcnt(0)
	s_barrier
	s_add_u32 s54, s54, 0x80
	s_addc_u32 s55, s55, 0
	s_add_u32 s56, s56, 0x80
	s_addc_u32 s57, s57, 0
	ds_read_b128 v[64:67], v156 offset:32768
	ds_read_b128 v[68:71], v158 offset:49152
	ds_read_b128 v[80:83], v159 offset:49152
	ds_read_b128 v[72:75], v157 offset:32768
	ds_read_b128 v[76:79], v158 offset:51200
	ds_read_b128 v[92:95], v159 offset:51200
	ds_read_b128 v[84:87], v158 offset:53248
	ds_read_b128 v[116:119], v159 offset:53248
	ds_read_b128 v[88:91], v158 offset:55296
	ds_read_b128 v[120:123], v159 offset:55296
	s_waitcnt lgkmcnt(8)
	v_mfma_f32_16x16x32_bf16 v[36:39], v[64:67], v[68:71], v[36:39]
	s_waitcnt lgkmcnt(5)
	v_mfma_f32_16x16x32_bf16 v[32:35], v[64:67], v[76:79], v[32:35]
	s_waitcnt lgkmcnt(3)
	s_add_u32 m0, s58, 0x0
	v_mfma_f32_16x16x32_bf16 v[28:31], v[64:67], v[84:87], v[28:31]
	global_load_lds_dwordx4 v152, s[54:55]
	s_waitcnt lgkmcnt(1)
	v_mfma_f32_16x16x32_bf16 v[24:27], v[64:67], v[88:91], v[24:27]
	ds_read_b128 v[64:67], v156 offset:34816
	ds_read_b128 v[124:127], v157 offset:34816
	s_waitcnt lgkmcnt(1)
	v_mfma_f32_16x16x32_bf16 v[8:11], v[64:67], v[68:71], v[8:11]
	s_add_u32 m0, m0, 0x400
	v_mfma_f32_16x16x32_bf16 v[4:7], v[64:67], v[76:79], v[4:7]
	global_load_lds_dwordx4 v153, s[54:55]
	v_mfma_f32_16x16x32_bf16 v[0:3], v[64:67], v[84:87], v[0:3]
	v_mfma_f32_16x16x32_bf16 v[20:23], v[64:67], v[88:91], v[20:23]
	ds_read_b128 v[64:67], v156 offset:36864
	ds_read_b128 v[128:131], v157 offset:36864
	s_waitcnt lgkmcnt(1)
	s_add_u32 m0, m0, 0x400
	v_mfma_f32_16x16x32_bf16 v[12:15], v[64:67], v[68:71], v[12:15]
	global_load_lds_dwordx4 v154, s[54:55]
	v_mfma_f32_16x16x32_bf16 v[16:19], v[64:67], v[76:79], v[16:19]
	v_mfma_f32_16x16x32_bf16 v[56:59], v[64:67], v[84:87], v[56:59]
	s_add_u32 m0, m0, 0x400
	v_mfma_f32_16x16x32_bf16 v[52:55], v[64:67], v[88:91], v[52:55]
	global_load_lds_dwordx4 v155, s[54:55]
	ds_read_b128 v[64:67], v156 offset:38912
	ds_read_b128 v[132:135], v157 offset:38912
	s_waitcnt lgkmcnt(1)
	v_mfma_f32_16x16x32_bf16 v[48:51], v[64:67], v[68:71], v[48:51]
	v_mfma_f32_16x16x32_bf16 v[44:47], v[64:67], v[76:79], v[44:47]
	s_add_u32 m0, m0, 0x3400
	v_mfma_f32_16x16x32_bf16 v[40:43], v[64:67], v[84:87], v[40:43]
	global_load_lds_dwordx4 v152, s[56:57]
	v_mfma_f32_16x16x32_bf16 v[60:63], v[64:67], v[88:91], v[60:63]
	v_mfma_f32_16x16x32_bf16 v[36:39], v[72:75], v[80:83], v[36:39]
	s_add_u32 m0, m0, 0x400
	v_mfma_f32_16x16x32_bf16 v[32:35], v[72:75], v[92:95], v[32:35]
	global_load_lds_dwordx4 v153, s[56:57]
	v_mfma_f32_16x16x32_bf16 v[28:31], v[72:75], v[116:119], v[28:31]
	v_mfma_f32_16x16x32_bf16 v[24:27], v[72:75], v[120:123], v[24:27]
	s_add_u32 m0, m0, 0x400
	v_mfma_f32_16x16x32_bf16 v[8:11], v[124:127], v[80:83], v[8:11]
	global_load_lds_dwordx4 v154, s[56:57]
	v_mfma_f32_16x16x32_bf16 v[4:7], v[124:127], v[92:95], v[4:7]
	v_mfma_f32_16x16x32_bf16 v[0:3], v[124:127], v[116:119], v[0:3]
	s_add_u32 m0, m0, 0x400
	v_mfma_f32_16x16x32_bf16 v[20:23], v[124:127], v[120:123], v[20:23]
	global_load_lds_dwordx4 v155, s[56:57]
	v_mfma_f32_16x16x32_bf16 v[12:15], v[128:131], v[80:83], v[12:15]
	s_waitcnt lgkmcnt(0)
	v_mfma_f32_16x16x32_bf16 v[48:51], v[132:135], v[80:83], v[48:51]
	v_mfma_f32_16x16x32_bf16 v[16:19], v[128:131], v[92:95], v[16:19]
	v_mfma_f32_16x16x32_bf16 v[44:47], v[132:135], v[92:95], v[44:47]
	v_mfma_f32_16x16x32_bf16 v[56:59], v[128:131], v[116:119], v[56:59]
	v_mfma_f32_16x16x32_bf16 v[52:55], v[128:131], v[120:123], v[52:55]
	v_mfma_f32_16x16x32_bf16 v[40:43], v[132:135], v[116:119], v[40:43]
	v_mfma_f32_16x16x32_bf16 v[60:63], v[132:135], v[120:123], v[60:63]
	s_waitcnt vmcnt(0)
	s_barrier
	s_add_i32 s59, s59, -1
	s_cmp_lg_u32 s59, 0
	s_cbranch_scc1 .Lg2_loop
	s_nop 7
	s_nop 7
	s_movk_i32 s4, 0x3a00
	s_add_i32 s6, s6, s92
	v_add_u32_e32 v68, s3, v111
	s_ashr_i32 s3, s2, 31
	v_lshl_add_u64 v[64:65], s[2:3], 2, v[100:101]
	v_mad_i64_i32 v[66:67], s[2:3], v68, s4, v[64:65]
	global_store_dword v[66:67], v36, off sc1
	global_store_dword v[66:67], v32, off offset:64 sc1
	global_store_dword v[66:67], v28, off offset:128 sc1
	global_store_dword v[66:67], v24, off offset:192 sc1
	v_or_b32_e32 v24, 1, v68
	v_mad_i64_i32 v[66:67], s[2:3], v24, s4, v[64:65]
	v_or_b32_e32 v24, 2, v68
	global_store_dword v[66:67], v37, off sc1
	global_store_dword v[66:67], v33, off offset:64 sc1
	global_store_dword v[66:67], v29, off offset:128 sc1
	global_store_dword v[66:67], v25, off offset:192 sc1
	v_mad_i64_i32 v[24:25], s[2:3], v24, s4, v[64:65]
	global_store_dword v[24:25], v38, off sc1
	global_store_dword v[24:25], v34, off offset:64 sc1
	global_store_dword v[24:25], v30, off offset:128 sc1
	global_store_dword v[24:25], v26, off offset:192 sc1
	v_or_b32_e32 v24, 3, v68
	v_mad_i64_i32 v[24:25], s[2:3], v24, s4, v[64:65]
	global_store_dword v[24:25], v39, off sc1
	global_store_dword v[24:25], v35, off offset:64 sc1
	global_store_dword v[24:25], v31, off offset:128 sc1
	global_store_dword v[24:25], v27, off offset:192 sc1
	v_or_b32_e32 v24, 16, v68
	v_mad_i64_i32 v[24:25], s[2:3], v24, s4, v[64:65]
	global_store_dword v[24:25], v8, off sc1
	global_store_dword v[24:25], v4, off offset:64 sc1
	global_store_dword v[24:25], v0, off offset:128 sc1
	global_store_dword v[24:25], v20, off offset:192 sc1
	v_or_b32_e32 v0, 17, v68
	v_mad_i64_i32 v[24:25], s[2:3], v0, s4, v[64:65]
	v_or_b32_e32 v0, 18, v68
	global_store_dword v[24:25], v9, off sc1
	global_store_dword v[24:25], v5, off offset:64 sc1
	global_store_dword v[24:25], v1, off offset:128 sc1
	global_store_dword v[24:25], v21, off offset:192 sc1
	v_mad_i64_i32 v[0:1], s[2:3], v0, s4, v[64:65]
	global_store_dword v[0:1], v10, off sc1
	global_store_dword v[0:1], v6, off offset:64 sc1
	global_store_dword v[0:1], v2, off offset:128 sc1
	global_store_dword v[0:1], v22, off offset:192 sc1
	v_or_b32_e32 v0, 19, v68
	v_mad_i64_i32 v[0:1], s[2:3], v0, s4, v[64:65]
	global_store_dword v[0:1], v11, off sc1
	global_store_dword v[0:1], v7, off offset:64 sc1
	global_store_dword v[0:1], v3, off offset:128 sc1
	global_store_dword v[0:1], v23, off offset:192 sc1
	v_or_b32_e32 v0, 32, v68
	v_mad_i64_i32 v[0:1], s[2:3], v0, s4, v[64:65]
	global_store_dword v[0:1], v12, off sc1
	global_store_dword v[0:1], v16, off offset:64 sc1
	global_store_dword v[0:1], v56, off offset:128 sc1
	global_store_dword v[0:1], v52, off offset:192 sc1
	v_or_b32_e32 v0, 33, v68
	v_mad_i64_i32 v[0:1], s[2:3], v0, s4, v[64:65]
	global_store_dword v[0:1], v13, off sc1
	global_store_dword v[0:1], v17, off offset:64 sc1
	global_store_dword v[0:1], v57, off offset:128 sc1
	global_store_dword v[0:1], v53, off offset:192 sc1
	v_or_b32_e32 v0, 34, v68
	v_mad_i64_i32 v[0:1], s[2:3], v0, s4, v[64:65]
	global_store_dword v[0:1], v14, off sc1
	global_store_dword v[0:1], v18, off offset:64 sc1
	global_store_dword v[0:1], v58, off offset:128 sc1
	global_store_dword v[0:1], v54, off offset:192 sc1
	v_or_b32_e32 v0, 35, v68
	v_mad_i64_i32 v[0:1], s[2:3], v0, s4, v[64:65]
	global_store_dword v[0:1], v15, off sc1
	global_store_dword v[0:1], v19, off offset:64 sc1
	global_store_dword v[0:1], v59, off offset:128 sc1
	global_store_dword v[0:1], v55, off offset:192 sc1
	v_or_b32_e32 v0, 48, v68
	v_mad_i64_i32 v[0:1], s[2:3], v0, s4, v[64:65]
	global_store_dword v[0:1], v48, off sc1
	global_store_dword v[0:1], v44, off offset:64 sc1
	global_store_dword v[0:1], v40, off offset:128 sc1
	s_nop 4
	global_store_dword v[0:1], v60, off offset:192 sc1
	v_or_b32_e32 v0, 49, v68
	v_mad_i64_i32 v[0:1], s[2:3], v0, s4, v[64:65]
	global_store_dword v[0:1], v49, off sc1
	global_store_dword v[0:1], v45, off offset:64 sc1
	global_store_dword v[0:1], v41, off offset:128 sc1
	global_store_dword v[0:1], v61, off offset:192 sc1
	v_or_b32_e32 v0, 50, v68
	v_mad_i64_i32 v[0:1], s[2:3], v0, s4, v[64:65]
	global_store_dword v[0:1], v50, off sc1
	global_store_dword v[0:1], v46, off offset:64 sc1
	global_store_dword v[0:1], v42, off offset:128 sc1
	global_store_dword v[0:1], v62, off offset:192 sc1
	v_or_b32_e32 v0, 51, v68
	v_mad_i64_i32 v[0:1], s[2:3], v0, s4, v[64:65]
	s_cmp_ge_i32 s6, s21
	global_store_dword v[0:1], v51, off sc1
	global_store_dword v[0:1], v47, off offset:64 sc1
	global_store_dword v[0:1], v43, off offset:128 sc1
	global_store_dword v[0:1], v63, off offset:192 sc1
	s_cbranch_scc0 .LBB0_259
